# UP projection prompt epilogue re-written by hand: DPP operands fused into v_fmac, packed f32 for lane-local math (same formula); plus OUT/DOWN residual loads hoisted
# speedup vs baseline: 1.0098x; 1.0098x over previous
.LBB0_1057:
	s_or_b64 exec, exec, s[20:21]
	s_waitcnt lgkmcnt(0)
	s_barrier
	v_readlane_b32 s0, v255, 21
	v_cmp_eq_u32_e64 s[40:41], 15, v226
	v_mov_b32_e32 v188, 0xbfb8aa3b
	v_mov_b32_e32 v189, 0xbfb8aa3b
	v_mov_b32_e32 v212, 1.0
	v_mov_b32_e32 v213, 1.0
	s_add_u32 s100, s6, 0x1d860000
	s_addc_u32 s101, s7, 0
	v_cndmask_b32_e64 v210, 0, v225, s[40:41]
	v_add3_u32 v210, s0, v210, v162
	v_add_u32_e32 v211, s63, v226
	v_cmp_gt_u32_e64 s[20:21], 2, v211
	s_and_b32 s1, s54, 7
	s_cmp_lg_u32 s1, 0
	s_cselect_b64 s[4:5], -1, 0
	v_lshl_add_u32 v211, s54, 8, v211
	v_mul_u32_u24_e32 v211, 0x1500, v211
	v_lshl_add_u32 v211, v172, 1, v211
	s_and_b64 s[20:21], s[20:21], s[4:5]
	v_mov_b32_e32 v162, 0
	v_mov_b32_e32 v163, 0
	v_mov_b32_e32 v164, 0
	v_mov_b32_e32 v165, 0
	v_mov_b32_e32 v166, 0
	v_mov_b32_e32 v167, 0
	v_mov_b32_e32 v168, 0
	v_mov_b32_e32 v169, 0
	s_andn2_b64 vcc, exec, s[16:17]
	s_cbranch_vccnz .Lup_pv0_skip
	ds_read_b128 v[166:169], v210
	ds_read_b128 v[162:165], v210 offset:16
.Lup_pv0_skip:
	v_add_u32_e32 v210, v210, v229
	s_waitcnt vmcnt(0) lgkmcnt(0)
	v_cndmask_b32_e64 v170, v150, v166, s[38:39]
	v_cndmask_b32_e64 v171, v151, v167, s[38:39]
	v_cndmask_b32_e64 v172, v152, v168, s[38:39]
	v_cndmask_b32_e64 v173, v153, v169, s[38:39]
	v_cndmask_b32_e64 v174, v146, v162, s[38:39]
	v_cndmask_b32_e64 v175, v147, v163, s[38:39]
	v_cndmask_b32_e64 v176, v148, v164, s[38:39]
	v_cndmask_b32_e64 v177, v149, v165, s[38:39]
	v_cndmask_b32_e64 v166, v150, v166, s[40:41]
	v_cndmask_b32_e64 v167, v151, v167, s[40:41]
	v_cndmask_b32_e64 v168, v152, v168, s[40:41]
	v_cndmask_b32_e64 v169, v153, v169, s[40:41]
	v_cndmask_b32_e64 v162, v146, v162, s[40:41]
	v_cndmask_b32_e64 v163, v147, v163, s[40:41]
	v_cndmask_b32_e64 v164, v148, v164, s[40:41]
	v_cndmask_b32_e64 v165, v149, v165, s[40:41]
	v_pk_fma_f32 v[178:179], v[126:127], v[150:151], v[130:131]
	v_pk_fma_f32 v[180:181], v[128:129], v[152:153], v[132:133]
	v_pk_fma_f32 v[182:183], v[118:119], v[146:147], v[110:111]
	v_pk_fma_f32 v[184:185], v[120:121], v[148:149], v[112:113]
	v_fmac_f32_dpp v178, v166, v134 row_ror:1 row_mask:0xf bank_mask:0xf
	v_fmac_f32_dpp v179, v167, v135 row_ror:1 row_mask:0xf bank_mask:0xf
	v_fmac_f32_dpp v180, v168, v136 row_ror:1 row_mask:0xf bank_mask:0xf
	v_fmac_f32_dpp v181, v169, v137 row_ror:1 row_mask:0xf bank_mask:0xf
	v_fmac_f32_dpp v182, v162, v114 row_ror:1 row_mask:0xf bank_mask:0xf
	v_fmac_f32_dpp v183, v163, v115 row_ror:1 row_mask:0xf bank_mask:0xf
	v_fmac_f32_dpp v184, v164, v116 row_ror:1 row_mask:0xf bank_mask:0xf
	v_fmac_f32_dpp v185, v165, v117 row_ror:1 row_mask:0xf bank_mask:0xf
	v_fmac_f32_dpp v178, v170, v122 row_ror:2 row_mask:0xf bank_mask:0xf
	v_fmac_f32_dpp v179, v171, v123 row_ror:2 row_mask:0xf bank_mask:0xf
	v_fmac_f32_dpp v180, v172, v124 row_ror:2 row_mask:0xf bank_mask:0xf
	v_fmac_f32_dpp v181, v173, v125 row_ror:2 row_mask:0xf bank_mask:0xf
	v_fmac_f32_dpp v182, v174, v106 row_ror:2 row_mask:0xf bank_mask:0xf
	v_fmac_f32_dpp v183, v175, v107 row_ror:2 row_mask:0xf bank_mask:0xf
	v_fmac_f32_dpp v184, v176, v108 row_ror:2 row_mask:0xf bank_mask:0xf
	v_fmac_f32_dpp v185, v177, v109 row_ror:2 row_mask:0xf bank_mask:0xf
	v_pk_mul_f32 v[166:167], v[178:179], v[188:189]
	v_pk_mul_f32 v[168:169], v[180:181], v[188:189]
	v_pk_mul_f32 v[162:163], v[182:183], v[188:189]
	v_pk_mul_f32 v[164:165], v[184:185], v[188:189]
	v_exp_f32_e32 v166, v166
	v_exp_f32_e32 v167, v167
	v_exp_f32_e32 v168, v168
	v_exp_f32_e32 v169, v169
	v_exp_f32_e32 v162, v162
	v_exp_f32_e32 v163, v163
	v_exp_f32_e32 v164, v164
	v_exp_f32_e32 v165, v165
	v_pk_add_f32 v[166:167], v[166:167], v[212:213]
	v_pk_add_f32 v[168:169], v[168:169], v[212:213]
	v_pk_add_f32 v[162:163], v[162:163], v[212:213]
	v_pk_add_f32 v[164:165], v[164:165], v[212:213]
	v_rcp_f32_e32 v166, v166
	v_rcp_f32_e32 v167, v167
	v_rcp_f32_e32 v168, v168
	v_rcp_f32_e32 v169, v169
	v_rcp_f32_e32 v162, v162
	v_rcp_f32_e32 v163, v163
	v_rcp_f32_e32 v164, v164
	v_rcp_f32_e32 v165, v165
	v_pk_mul_f32 v[170:171], v[178:179], v[166:167]
	v_pk_mul_f32 v[172:173], v[180:181], v[168:169]
	v_pk_mul_f32 v[174:175], v[182:183], v[162:163]
	v_pk_mul_f32 v[176:177], v[184:185], v[164:165]
	v_pk_mul_f32 v[170:171], v[158:159], v[170:171]
	v_pk_mul_f32 v[172:173], v[160:161], v[172:173]
	v_pk_mul_f32 v[174:175], v[154:155], v[174:175]
	v_pk_mul_f32 v[176:177], v[156:157], v[176:177]
	v_cvt_pk_bf16_f32 v178, v170, v171
	v_cvt_pk_bf16_f32 v179, v172, v173
	v_cvt_pk_bf16_f32 v180, v174, v175
	v_cvt_pk_bf16_f32 v181, v176, v177
	s_andn2_b64 exec, exec, s[20:21]
	global_store_dwordx4 v211, v[178:181], s[100:101]
	s_mov_b64 exec, s[20:21]
	s_cbranch_execz .Lup_nodefer
	v_lshl_add_u32 v162, v227, 3, s64
	v_add_u32_e32 v162, s24, v162
	v_add_u32_e32 v163, s63, v226
	v_lshl_add_u32 v163, s54, 1, v163
	v_mul_u32_u24_e32 v163, 0x2a00, v163
	v_lshl_add_u32 v162, v162, 2, v163
	s_add_u32 s4, s6, 0x1d460000
	s_addc_u32 s5, s7, 0
	global_store_dwordx4 v162, v[150:153], s[4:5]
	global_store_dwordx4 v162, v[146:149], s[4:5] offset:16
	s_add_u32 s4, s6, 0x1d660000
	s_addc_u32 s5, s7, 0
	global_store_dwordx4 v162, v[158:161], s[4:5]
	global_store_dwordx4 v162, v[154:157], s[4:5] offset:16
.Lup_nodefer:
	s_mov_b64 exec, -1
	v_cndmask_b32_e64 v170, v102, v150, s[38:39]
	v_cndmask_b32_e64 v171, v103, v151, s[38:39]
	v_cndmask_b32_e64 v172, v104, v152, s[38:39]
	v_cndmask_b32_e64 v173, v105, v153, s[38:39]
	v_cndmask_b32_e64 v174, v98, v146, s[38:39]
	v_cndmask_b32_e64 v175, v99, v147, s[38:39]
	v_cndmask_b32_e64 v176, v100, v148, s[38:39]
	v_cndmask_b32_e64 v177, v101, v149, s[38:39]
	v_cndmask_b32_e64 v166, v102, v150, s[40:41]
	v_cndmask_b32_e64 v167, v103, v151, s[40:41]
	v_cndmask_b32_e64 v168, v104, v152, s[40:41]
	v_cndmask_b32_e64 v169, v105, v153, s[40:41]
	v_cndmask_b32_e64 v162, v98, v146, s[40:41]
	v_cndmask_b32_e64 v163, v99, v147, s[40:41]
	v_cndmask_b32_e64 v164, v100, v148, s[40:41]
	v_cndmask_b32_e64 v165, v101, v149, s[40:41]
	ds_read_b128 v[158:161], v210
	ds_read_b128 v[154:157], v210 offset:16
	v_pk_fma_f32 v[178:179], v[126:127], v[102:103], v[130:131]
	v_pk_fma_f32 v[180:181], v[128:129], v[104:105], v[132:133]
	v_pk_fma_f32 v[182:183], v[118:119], v[98:99], v[110:111]
	v_pk_fma_f32 v[184:185], v[120:121], v[100:101], v[112:113]
	v_fmac_f32_dpp v178, v166, v134 row_ror:1 row_mask:0xf bank_mask:0xf
	v_fmac_f32_dpp v179, v167, v135 row_ror:1 row_mask:0xf bank_mask:0xf
	v_fmac_f32_dpp v180, v168, v136 row_ror:1 row_mask:0xf bank_mask:0xf
	v_fmac_f32_dpp v181, v169, v137 row_ror:1 row_mask:0xf bank_mask:0xf
	v_fmac_f32_dpp v182, v162, v114 row_ror:1 row_mask:0xf bank_mask:0xf
	v_fmac_f32_dpp v183, v163, v115 row_ror:1 row_mask:0xf bank_mask:0xf
	v_fmac_f32_dpp v184, v164, v116 row_ror:1 row_mask:0xf bank_mask:0xf
	v_fmac_f32_dpp v185, v165, v117 row_ror:1 row_mask:0xf bank_mask:0xf
	v_fmac_f32_dpp v178, v170, v122 row_ror:2 row_mask:0xf bank_mask:0xf
	v_fmac_f32_dpp v179, v171, v123 row_ror:2 row_mask:0xf bank_mask:0xf
	v_fmac_f32_dpp v180, v172, v124 row_ror:2 row_mask:0xf bank_mask:0xf
	v_fmac_f32_dpp v181, v173, v125 row_ror:2 row_mask:0xf bank_mask:0xf
	v_fmac_f32_dpp v182, v174, v106 row_ror:2 row_mask:0xf bank_mask:0xf
	v_fmac_f32_dpp v183, v175, v107 row_ror:2 row_mask:0xf bank_mask:0xf
	v_fmac_f32_dpp v184, v176, v108 row_ror:2 row_mask:0xf bank_mask:0xf
	v_fmac_f32_dpp v185, v177, v109 row_ror:2 row_mask:0xf bank_mask:0xf
	v_pk_mul_f32 v[166:167], v[178:179], v[188:189]
	v_pk_mul_f32 v[168:169], v[180:181], v[188:189]
	v_pk_mul_f32 v[162:163], v[182:183], v[188:189]
	v_pk_mul_f32 v[164:165], v[184:185], v[188:189]
	v_exp_f32_e32 v166, v166
	v_exp_f32_e32 v167, v167
	v_exp_f32_e32 v168, v168
	v_exp_f32_e32 v169, v169
	v_exp_f32_e32 v162, v162
	v_exp_f32_e32 v163, v163
	v_exp_f32_e32 v164, v164
	v_exp_f32_e32 v165, v165
	v_pk_add_f32 v[166:167], v[166:167], v[212:213]
	v_pk_add_f32 v[168:169], v[168:169], v[212:213]
	v_pk_add_f32 v[162:163], v[162:163], v[212:213]
	v_pk_add_f32 v[164:165], v[164:165], v[212:213]
	v_rcp_f32_e32 v166, v166
	v_rcp_f32_e32 v167, v167
	v_rcp_f32_e32 v168, v168
	v_rcp_f32_e32 v169, v169
	v_rcp_f32_e32 v162, v162
	v_rcp_f32_e32 v163, v163
	v_rcp_f32_e32 v164, v164
	v_rcp_f32_e32 v165, v165
	v_pk_mul_f32 v[170:171], v[178:179], v[166:167]
	v_pk_mul_f32 v[172:173], v[180:181], v[168:169]
	v_pk_mul_f32 v[174:175], v[182:183], v[162:163]
	v_pk_mul_f32 v[176:177], v[184:185], v[164:165]
	v_pk_mul_f32 v[170:171], v[142:143], v[170:171]
	v_pk_mul_f32 v[172:173], v[144:145], v[172:173]
	v_pk_mul_f32 v[174:175], v[138:139], v[174:175]
	v_pk_mul_f32 v[176:177], v[140:141], v[176:177]
	v_cvt_pk_bf16_f32 v178, v170, v171
	v_cvt_pk_bf16_f32 v179, v172, v173
	v_cvt_pk_bf16_f32 v180, v174, v175
	v_cvt_pk_bf16_f32 v181, v176, v177
	v_add_u32_e32 v182, 0x15000, v211
	global_store_dwordx4 v182, v[178:181], s[100:101]
	v_cndmask_b32_e64 v170, v86, v102, s[38:39]
	v_cndmask_b32_e64 v171, v87, v103, s[38:39]
	v_cndmask_b32_e64 v172, v88, v104, s[38:39]
	v_cndmask_b32_e64 v173, v89, v105, s[38:39]
	v_cndmask_b32_e64 v174, v82, v98, s[38:39]
	v_cndmask_b32_e64 v175, v83, v99, s[38:39]
	v_cndmask_b32_e64 v176, v84, v100, s[38:39]
	v_cndmask_b32_e64 v177, v85, v101, s[38:39]
	v_cndmask_b32_e64 v166, v86, v102, s[40:41]
	v_cndmask_b32_e64 v167, v87, v103, s[40:41]
	v_cndmask_b32_e64 v168, v88, v104, s[40:41]
	v_cndmask_b32_e64 v169, v89, v105, s[40:41]
	v_cndmask_b32_e64 v162, v82, v98, s[40:41]
	v_cndmask_b32_e64 v163, v83, v99, s[40:41]
	v_cndmask_b32_e64 v164, v84, v100, s[40:41]
	v_cndmask_b32_e64 v165, v85, v101, s[40:41]
	v_pk_fma_f32 v[178:179], v[126:127], v[86:87], v[130:131]
	v_pk_fma_f32 v[180:181], v[128:129], v[88:89], v[132:133]
	v_pk_fma_f32 v[182:183], v[118:119], v[82:83], v[110:111]
	v_pk_fma_f32 v[184:185], v[120:121], v[84:85], v[112:113]
	v_fmac_f32_dpp v178, v166, v134 row_ror:1 row_mask:0xf bank_mask:0xf
	v_fmac_f32_dpp v179, v167, v135 row_ror:1 row_mask:0xf bank_mask:0xf
	v_fmac_f32_dpp v180, v168, v136 row_ror:1 row_mask:0xf bank_mask:0xf
	v_fmac_f32_dpp v181, v169, v137 row_ror:1 row_mask:0xf bank_mask:0xf
	v_fmac_f32_dpp v182, v162, v114 row_ror:1 row_mask:0xf bank_mask:0xf
	v_fmac_f32_dpp v183, v163, v115 row_ror:1 row_mask:0xf bank_mask:0xf
	v_fmac_f32_dpp v184, v164, v116 row_ror:1 row_mask:0xf bank_mask:0xf
	v_fmac_f32_dpp v185, v165, v117 row_ror:1 row_mask:0xf bank_mask:0xf
	v_fmac_f32_dpp v178, v170, v122 row_ror:2 row_mask:0xf bank_mask:0xf
	v_fmac_f32_dpp v179, v171, v123 row_ror:2 row_mask:0xf bank_mask:0xf
	v_fmac_f32_dpp v180, v172, v124 row_ror:2 row_mask:0xf bank_mask:0xf
	v_fmac_f32_dpp v181, v173, v125 row_ror:2 row_mask:0xf bank_mask:0xf
	v_fmac_f32_dpp v182, v174, v106 row_ror:2 row_mask:0xf bank_mask:0xf
	v_fmac_f32_dpp v183, v175, v107 row_ror:2 row_mask:0xf bank_mask:0xf
	v_fmac_f32_dpp v184, v176, v108 row_ror:2 row_mask:0xf bank_mask:0xf
	v_fmac_f32_dpp v185, v177, v109 row_ror:2 row_mask:0xf bank_mask:0xf
	v_pk_mul_f32 v[166:167], v[178:179], v[188:189]
	v_pk_mul_f32 v[168:169], v[180:181], v[188:189]
	v_pk_mul_f32 v[162:163], v[182:183], v[188:189]
	v_pk_mul_f32 v[164:165], v[184:185], v[188:189]
	v_exp_f32_e32 v166, v166
	v_exp_f32_e32 v167, v167
	v_exp_f32_e32 v168, v168
	v_exp_f32_e32 v169, v169
	v_exp_f32_e32 v162, v162
	v_exp_f32_e32 v163, v163
	v_exp_f32_e32 v164, v164
	v_exp_f32_e32 v165, v165
	v_pk_add_f32 v[166:167], v[166:167], v[212:213]
	v_pk_add_f32 v[168:169], v[168:169], v[212:213]
	v_pk_add_f32 v[162:163], v[162:163], v[212:213]
	v_pk_add_f32 v[164:165], v[164:165], v[212:213]
	v_rcp_f32_e32 v166, v166
	v_rcp_f32_e32 v167, v167
	v_rcp_f32_e32 v168, v168
	v_rcp_f32_e32 v169, v169
	v_rcp_f32_e32 v162, v162
	v_rcp_f32_e32 v163, v163
	v_rcp_f32_e32 v164, v164
	v_rcp_f32_e32 v165, v165
	v_pk_mul_f32 v[170:171], v[178:179], v[166:167]
	v_pk_mul_f32 v[172:173], v[180:181], v[168:169]
	v_pk_mul_f32 v[174:175], v[182:183], v[162:163]
	v_pk_mul_f32 v[176:177], v[184:185], v[164:165]
	v_pk_mul_f32 v[170:171], v[94:95], v[170:171]
	v_pk_mul_f32 v[172:173], v[96:97], v[172:173]
	v_pk_mul_f32 v[174:175], v[90:91], v[174:175]
	v_pk_mul_f32 v[176:177], v[92:93], v[176:177]
	v_cvt_pk_bf16_f32 v178, v170, v171
	v_cvt_pk_bf16_f32 v179, v172, v173
	v_cvt_pk_bf16_f32 v180, v174, v175
	v_cvt_pk_bf16_f32 v181, v176, v177
	v_add_u32_e32 v182, 0x2a000, v211
	global_store_dwordx4 v182, v[178:181], s[100:101]
	v_cndmask_b32_e64 v170, v74, v86, s[38:39]
	v_cndmask_b32_e64 v171, v75, v87, s[38:39]
	v_cndmask_b32_e64 v172, v76, v88, s[38:39]
	v_cndmask_b32_e64 v173, v77, v89, s[38:39]
	v_cndmask_b32_e64 v174, v70, v82, s[38:39]
	v_cndmask_b32_e64 v175, v71, v83, s[38:39]
	v_cndmask_b32_e64 v176, v72, v84, s[38:39]
	v_cndmask_b32_e64 v177, v73, v85, s[38:39]
	v_cndmask_b32_e64 v166, v74, v86, s[40:41]
	v_cndmask_b32_e64 v167, v75, v87, s[40:41]
	v_cndmask_b32_e64 v168, v76, v88, s[40:41]
	v_cndmask_b32_e64 v169, v77, v89, s[40:41]
	v_cndmask_b32_e64 v162, v70, v82, s[40:41]
	v_cndmask_b32_e64 v163, v71, v83, s[40:41]
	v_cndmask_b32_e64 v164, v72, v84, s[40:41]
	v_cndmask_b32_e64 v165, v73, v85, s[40:41]
	v_pk_fma_f32 v[178:179], v[126:127], v[74:75], v[130:131]
	v_pk_fma_f32 v[180:181], v[128:129], v[76:77], v[132:133]
	v_pk_fma_f32 v[182:183], v[118:119], v[70:71], v[110:111]
	v_pk_fma_f32 v[184:185], v[120:121], v[72:73], v[112:113]
	v_fmac_f32_dpp v178, v166, v134 row_ror:1 row_mask:0xf bank_mask:0xf
	v_fmac_f32_dpp v179, v167, v135 row_ror:1 row_mask:0xf bank_mask:0xf
	v_fmac_f32_dpp v180, v168, v136 row_ror:1 row_mask:0xf bank_mask:0xf
	v_fmac_f32_dpp v181, v169, v137 row_ror:1 row_mask:0xf bank_mask:0xf
	v_fmac_f32_dpp v182, v162, v114 row_ror:1 row_mask:0xf bank_mask:0xf
	v_fmac_f32_dpp v183, v163, v115 row_ror:1 row_mask:0xf bank_mask:0xf
	v_fmac_f32_dpp v184, v164, v116 row_ror:1 row_mask:0xf bank_mask:0xf
	v_fmac_f32_dpp v185, v165, v117 row_ror:1 row_mask:0xf bank_mask:0xf
	v_fmac_f32_dpp v178, v170, v122 row_ror:2 row_mask:0xf bank_mask:0xf
	v_fmac_f32_dpp v179, v171, v123 row_ror:2 row_mask:0xf bank_mask:0xf
	v_fmac_f32_dpp v180, v172, v124 row_ror:2 row_mask:0xf bank_mask:0xf
	v_fmac_f32_dpp v181, v173, v125 row_ror:2 row_mask:0xf bank_mask:0xf
	v_fmac_f32_dpp v182, v174, v106 row_ror:2 row_mask:0xf bank_mask:0xf
	v_fmac_f32_dpp v183, v175, v107 row_ror:2 row_mask:0xf bank_mask:0xf
	v_fmac_f32_dpp v184, v176, v108 row_ror:2 row_mask:0xf bank_mask:0xf
	v_fmac_f32_dpp v185, v177, v109 row_ror:2 row_mask:0xf bank_mask:0xf
	v_pk_mul_f32 v[166:167], v[178:179], v[188:189]
	v_pk_mul_f32 v[168:169], v[180:181], v[188:189]
	v_pk_mul_f32 v[162:163], v[182:183], v[188:189]
	v_pk_mul_f32 v[164:165], v[184:185], v[188:189]
	v_exp_f32_e32 v166, v166
	v_exp_f32_e32 v167, v167
	v_exp_f32_e32 v168, v168
	v_exp_f32_e32 v169, v169
	v_exp_f32_e32 v162, v162
	v_exp_f32_e32 v163, v163
	v_exp_f32_e32 v164, v164
	v_exp_f32_e32 v165, v165
	v_pk_add_f32 v[166:167], v[166:167], v[212:213]
	v_pk_add_f32 v[168:169], v[168:169], v[212:213]
	v_pk_add_f32 v[162:163], v[162:163], v[212:213]
	v_pk_add_f32 v[164:165], v[164:165], v[212:213]
	v_rcp_f32_e32 v166, v166
	v_rcp_f32_e32 v167, v167
	v_rcp_f32_e32 v168, v168
	v_rcp_f32_e32 v169, v169
	v_rcp_f32_e32 v162, v162
	v_rcp_f32_e32 v163, v163
	v_rcp_f32_e32 v164, v164
	v_rcp_f32_e32 v165, v165
	v_pk_mul_f32 v[170:171], v[178:179], v[166:167]
	v_pk_mul_f32 v[172:173], v[180:181], v[168:169]
	v_pk_mul_f32 v[174:175], v[182:183], v[162:163]
	v_pk_mul_f32 v[176:177], v[184:185], v[164:165]
	v_pk_mul_f32 v[170:171], v[78:79], v[170:171]
	v_pk_mul_f32 v[172:173], v[80:81], v[172:173]
	v_pk_mul_f32 v[174:175], v[66:67], v[174:175]
	v_pk_mul_f32 v[176:177], v[68:69], v[176:177]
	v_cvt_pk_bf16_f32 v178, v170, v171
	v_cvt_pk_bf16_f32 v179, v172, v173
	v_cvt_pk_bf16_f32 v180, v174, v175
	v_cvt_pk_bf16_f32 v181, v176, v177
	v_add_u32_e32 v182, 0x3f000, v211
	global_store_dwordx4 v182, v[178:181], s[100:101]
	s_waitcnt lgkmcnt(0)
	v_cndmask_b32_e64 v170, v54, v158, s[38:39]
	v_cndmask_b32_e64 v171, v55, v159, s[38:39]
	v_cndmask_b32_e64 v172, v56, v160, s[38:39]
	v_cndmask_b32_e64 v173, v57, v161, s[38:39]
	v_cndmask_b32_e64 v174, v46, v154, s[38:39]
	v_cndmask_b32_e64 v175, v47, v155, s[38:39]
	v_cndmask_b32_e64 v176, v48, v156, s[38:39]
	v_cndmask_b32_e64 v177, v49, v157, s[38:39]
	v_cndmask_b32_e64 v166, v54, v158, s[40:41]
	v_cndmask_b32_e64 v167, v55, v159, s[40:41]
	v_cndmask_b32_e64 v168, v56, v160, s[40:41]
	v_cndmask_b32_e64 v169, v57, v161, s[40:41]
	v_cndmask_b32_e64 v162, v46, v154, s[40:41]
	v_cndmask_b32_e64 v163, v47, v155, s[40:41]
	v_cndmask_b32_e64 v164, v48, v156, s[40:41]
	v_cndmask_b32_e64 v165, v49, v157, s[40:41]
	v_pk_fma_f32 v[178:179], v[126:127], v[54:55], v[130:131]
	v_pk_fma_f32 v[180:181], v[128:129], v[56:57], v[132:133]
	v_pk_fma_f32 v[182:183], v[118:119], v[46:47], v[110:111]
	v_pk_fma_f32 v[184:185], v[120:121], v[48:49], v[112:113]
	v_fmac_f32_dpp v178, v166, v134 row_ror:1 row_mask:0xf bank_mask:0xf
	v_fmac_f32_dpp v179, v167, v135 row_ror:1 row_mask:0xf bank_mask:0xf
	v_fmac_f32_dpp v180, v168, v136 row_ror:1 row_mask:0xf bank_mask:0xf
	v_fmac_f32_dpp v181, v169, v137 row_ror:1 row_mask:0xf bank_mask:0xf
	v_fmac_f32_dpp v182, v162, v114 row_ror:1 row_mask:0xf bank_mask:0xf
	v_fmac_f32_dpp v183, v163, v115 row_ror:1 row_mask:0xf bank_mask:0xf
	v_fmac_f32_dpp v184, v164, v116 row_ror:1 row_mask:0xf bank_mask:0xf
	v_fmac_f32_dpp v185, v165, v117 row_ror:1 row_mask:0xf bank_mask:0xf
	v_fmac_f32_dpp v178, v170, v122 row_ror:2 row_mask:0xf bank_mask:0xf
	v_fmac_f32_dpp v179, v171, v123 row_ror:2 row_mask:0xf bank_mask:0xf
	v_fmac_f32_dpp v180, v172, v124 row_ror:2 row_mask:0xf bank_mask:0xf
	v_fmac_f32_dpp v181, v173, v125 row_ror:2 row_mask:0xf bank_mask:0xf
	v_fmac_f32_dpp v182, v174, v106 row_ror:2 row_mask:0xf bank_mask:0xf
	v_fmac_f32_dpp v183, v175, v107 row_ror:2 row_mask:0xf bank_mask:0xf
	v_fmac_f32_dpp v184, v176, v108 row_ror:2 row_mask:0xf bank_mask:0xf
	v_fmac_f32_dpp v185, v177, v109 row_ror:2 row_mask:0xf bank_mask:0xf
	v_pk_mul_f32 v[166:167], v[178:179], v[188:189]
	v_pk_mul_f32 v[168:169], v[180:181], v[188:189]
	v_pk_mul_f32 v[162:163], v[182:183], v[188:189]
	v_pk_mul_f32 v[164:165], v[184:185], v[188:189]
	v_exp_f32_e32 v166, v166
	v_exp_f32_e32 v167, v167
	v_exp_f32_e32 v168, v168
	v_exp_f32_e32 v169, v169
	v_exp_f32_e32 v162, v162
	v_exp_f32_e32 v163, v163
	v_exp_f32_e32 v164, v164
	v_exp_f32_e32 v165, v165
	v_pk_add_f32 v[166:167], v[166:167], v[212:213]
	v_pk_add_f32 v[168:169], v[168:169], v[212:213]
	v_pk_add_f32 v[162:163], v[162:163], v[212:213]
	v_pk_add_f32 v[164:165], v[164:165], v[212:213]
	v_rcp_f32_e32 v166, v166
	v_rcp_f32_e32 v167, v167
	v_rcp_f32_e32 v168, v168
	v_rcp_f32_e32 v169, v169
	v_rcp_f32_e32 v162, v162
	v_rcp_f32_e32 v163, v163
	v_rcp_f32_e32 v164, v164
	v_rcp_f32_e32 v165, v165
	v_pk_mul_f32 v[170:171], v[178:179], v[166:167]
	v_pk_mul_f32 v[172:173], v[180:181], v[168:169]
	v_pk_mul_f32 v[174:175], v[182:183], v[162:163]
	v_pk_mul_f32 v[176:177], v[184:185], v[164:165]
	v_pk_mul_f32 v[170:171], v[62:63], v[170:171]
	v_pk_mul_f32 v[172:173], v[64:65], v[172:173]
	v_pk_mul_f32 v[174:175], v[58:59], v[174:175]
	v_pk_mul_f32 v[176:177], v[60:61], v[176:177]
	v_cvt_pk_bf16_f32 v178, v170, v171
	v_cvt_pk_bf16_f32 v179, v172, v173
	v_cvt_pk_bf16_f32 v180, v174, v175
	v_cvt_pk_bf16_f32 v181, v176, v177
	v_add_u32_e32 v182, 0xa8000, v211
	global_store_dwordx4 v182, v[178:181], s[100:101]
	v_cndmask_b32_e64 v170, v38, v54, s[38:39]
	v_cndmask_b32_e64 v171, v39, v55, s[38:39]
	v_cndmask_b32_e64 v172, v40, v56, s[38:39]
	v_cndmask_b32_e64 v173, v41, v57, s[38:39]
	v_cndmask_b32_e64 v174, v30, v46, s[38:39]
	v_cndmask_b32_e64 v175, v31, v47, s[38:39]
	v_cndmask_b32_e64 v176, v32, v48, s[38:39]
	v_cndmask_b32_e64 v177, v33, v49, s[38:39]
	v_cndmask_b32_e64 v166, v38, v54, s[40:41]
	v_cndmask_b32_e64 v167, v39, v55, s[40:41]
	v_cndmask_b32_e64 v168, v40, v56, s[40:41]
	v_cndmask_b32_e64 v169, v41, v57, s[40:41]
	v_cndmask_b32_e64 v162, v30, v46, s[40:41]
	v_cndmask_b32_e64 v163, v31, v47, s[40:41]
	v_cndmask_b32_e64 v164, v32, v48, s[40:41]
	v_cndmask_b32_e64 v165, v33, v49, s[40:41]
	v_pk_fma_f32 v[178:179], v[126:127], v[38:39], v[130:131]
	v_pk_fma_f32 v[180:181], v[128:129], v[40:41], v[132:133]
	v_pk_fma_f32 v[182:183], v[118:119], v[30:31], v[110:111]
	v_pk_fma_f32 v[184:185], v[120:121], v[32:33], v[112:113]
	v_fmac_f32_dpp v178, v166, v134 row_ror:1 row_mask:0xf bank_mask:0xf
	v_fmac_f32_dpp v179, v167, v135 row_ror:1 row_mask:0xf bank_mask:0xf
	v_fmac_f32_dpp v180, v168, v136 row_ror:1 row_mask:0xf bank_mask:0xf
	v_fmac_f32_dpp v181, v169, v137 row_ror:1 row_mask:0xf bank_mask:0xf
	v_fmac_f32_dpp v182, v162, v114 row_ror:1 row_mask:0xf bank_mask:0xf
	v_fmac_f32_dpp v183, v163, v115 row_ror:1 row_mask:0xf bank_mask:0xf
	v_fmac_f32_dpp v184, v164, v116 row_ror:1 row_mask:0xf bank_mask:0xf
	v_fmac_f32_dpp v185, v165, v117 row_ror:1 row_mask:0xf bank_mask:0xf
	v_fmac_f32_dpp v178, v170, v122 row_ror:2 row_mask:0xf bank_mask:0xf
	v_fmac_f32_dpp v179, v171, v123 row_ror:2 row_mask:0xf bank_mask:0xf
	v_fmac_f32_dpp v180, v172, v124 row_ror:2 row_mask:0xf bank_mask:0xf
	v_fmac_f32_dpp v181, v173, v125 row_ror:2 row_mask:0xf bank_mask:0xf
	v_fmac_f32_dpp v182, v174, v106 row_ror:2 row_mask:0xf bank_mask:0xf
	v_fmac_f32_dpp v183, v175, v107 row_ror:2 row_mask:0xf bank_mask:0xf
	v_fmac_f32_dpp v184, v176, v108 row_ror:2 row_mask:0xf bank_mask:0xf
	v_fmac_f32_dpp v185, v177, v109 row_ror:2 row_mask:0xf bank_mask:0xf
	v_pk_mul_f32 v[166:167], v[178:179], v[188:189]
	v_pk_mul_f32 v[168:169], v[180:181], v[188:189]
	v_pk_mul_f32 v[162:163], v[182:183], v[188:189]
	v_pk_mul_f32 v[164:165], v[184:185], v[188:189]
	v_exp_f32_e32 v166, v166
	v_exp_f32_e32 v167, v167
	v_exp_f32_e32 v168, v168
	v_exp_f32_e32 v169, v169
	v_exp_f32_e32 v162, v162
	v_exp_f32_e32 v163, v163
	v_exp_f32_e32 v164, v164
	v_exp_f32_e32 v165, v165
	v_pk_add_f32 v[166:167], v[166:167], v[212:213]
	v_pk_add_f32 v[168:169], v[168:169], v[212:213]
	v_pk_add_f32 v[162:163], v[162:163], v[212:213]
	v_pk_add_f32 v[164:165], v[164:165], v[212:213]
	v_rcp_f32_e32 v166, v166
	v_rcp_f32_e32 v167, v167
	v_rcp_f32_e32 v168, v168
	v_rcp_f32_e32 v169, v169
	v_rcp_f32_e32 v162, v162
	v_rcp_f32_e32 v163, v163
	v_rcp_f32_e32 v164, v164
	v_rcp_f32_e32 v165, v165
	v_pk_mul_f32 v[170:171], v[178:179], v[166:167]
	v_pk_mul_f32 v[172:173], v[180:181], v[168:169]
	v_pk_mul_f32 v[174:175], v[182:183], v[162:163]
	v_pk_mul_f32 v[176:177], v[184:185], v[164:165]
	v_pk_mul_f32 v[170:171], v[50:51], v[170:171]
	v_pk_mul_f32 v[172:173], v[52:53], v[172:173]
	v_pk_mul_f32 v[174:175], v[42:43], v[174:175]
	v_pk_mul_f32 v[176:177], v[44:45], v[176:177]
	v_cvt_pk_bf16_f32 v178, v170, v171
	v_cvt_pk_bf16_f32 v179, v172, v173
	v_cvt_pk_bf16_f32 v180, v174, v175
	v_cvt_pk_bf16_f32 v181, v176, v177
	v_add_u32_e32 v182, 0xbd000, v211
	global_store_dwordx4 v182, v[178:181], s[100:101]
	v_cndmask_b32_e64 v170, v22, v38, s[38:39]
	v_cndmask_b32_e64 v171, v23, v39, s[38:39]
	v_cndmask_b32_e64 v172, v24, v40, s[38:39]
	v_cndmask_b32_e64 v173, v25, v41, s[38:39]
	v_cndmask_b32_e64 v174, v10, v30, s[38:39]
	v_cndmask_b32_e64 v175, v11, v31, s[38:39]
	v_cndmask_b32_e64 v176, v12, v32, s[38:39]
	v_cndmask_b32_e64 v177, v13, v33, s[38:39]
	v_cndmask_b32_e64 v166, v22, v38, s[40:41]
	v_cndmask_b32_e64 v167, v23, v39, s[40:41]
	v_cndmask_b32_e64 v168, v24, v40, s[40:41]
	v_cndmask_b32_e64 v169, v25, v41, s[40:41]
	v_cndmask_b32_e64 v162, v10, v30, s[40:41]
	v_cndmask_b32_e64 v163, v11, v31, s[40:41]
	v_cndmask_b32_e64 v164, v12, v32, s[40:41]
	v_cndmask_b32_e64 v165, v13, v33, s[40:41]
	v_pk_fma_f32 v[178:179], v[126:127], v[22:23], v[130:131]
	v_pk_fma_f32 v[180:181], v[128:129], v[24:25], v[132:133]
	v_pk_fma_f32 v[182:183], v[118:119], v[10:11], v[110:111]
	v_pk_fma_f32 v[184:185], v[120:121], v[12:13], v[112:113]
	v_fmac_f32_dpp v178, v166, v134 row_ror:1 row_mask:0xf bank_mask:0xf
	v_fmac_f32_dpp v179, v167, v135 row_ror:1 row_mask:0xf bank_mask:0xf
	v_fmac_f32_dpp v180, v168, v136 row_ror:1 row_mask:0xf bank_mask:0xf
	v_fmac_f32_dpp v181, v169, v137 row_ror:1 row_mask:0xf bank_mask:0xf
	v_fmac_f32_dpp v182, v162, v114 row_ror:1 row_mask:0xf bank_mask:0xf
	v_fmac_f32_dpp v183, v163, v115 row_ror:1 row_mask:0xf bank_mask:0xf
	v_fmac_f32_dpp v184, v164, v116 row_ror:1 row_mask:0xf bank_mask:0xf
	v_fmac_f32_dpp v185, v165, v117 row_ror:1 row_mask:0xf bank_mask:0xf
	v_fmac_f32_dpp v178, v170, v122 row_ror:2 row_mask:0xf bank_mask:0xf
	v_fmac_f32_dpp v179, v171, v123 row_ror:2 row_mask:0xf bank_mask:0xf
	v_fmac_f32_dpp v180, v172, v124 row_ror:2 row_mask:0xf bank_mask:0xf
	v_fmac_f32_dpp v181, v173, v125 row_ror:2 row_mask:0xf bank_mask:0xf
	v_fmac_f32_dpp v182, v174, v106 row_ror:2 row_mask:0xf bank_mask:0xf
	v_fmac_f32_dpp v183, v175, v107 row_ror:2 row_mask:0xf bank_mask:0xf
	v_fmac_f32_dpp v184, v176, v108 row_ror:2 row_mask:0xf bank_mask:0xf
	v_fmac_f32_dpp v185, v177, v109 row_ror:2 row_mask:0xf bank_mask:0xf
	v_pk_mul_f32 v[166:167], v[178:179], v[188:189]
	v_pk_mul_f32 v[168:169], v[180:181], v[188:189]
	v_pk_mul_f32 v[162:163], v[182:183], v[188:189]
	v_pk_mul_f32 v[164:165], v[184:185], v[188:189]
	v_exp_f32_e32 v166, v166
	v_exp_f32_e32 v167, v167
	v_exp_f32_e32 v168, v168
	v_exp_f32_e32 v169, v169
	v_exp_f32_e32 v162, v162
	v_exp_f32_e32 v163, v163
	v_exp_f32_e32 v164, v164
	v_exp_f32_e32 v165, v165
	v_pk_add_f32 v[166:167], v[166:167], v[212:213]
	v_pk_add_f32 v[168:169], v[168:169], v[212:213]
	v_pk_add_f32 v[162:163], v[162:163], v[212:213]
	v_pk_add_f32 v[164:165], v[164:165], v[212:213]
	v_rcp_f32_e32 v166, v166
	v_rcp_f32_e32 v167, v167
	v_rcp_f32_e32 v168, v168
	v_rcp_f32_e32 v169, v169
	v_rcp_f32_e32 v162, v162
	v_rcp_f32_e32 v163, v163
	v_rcp_f32_e32 v164, v164
	v_rcp_f32_e32 v165, v165
	v_pk_mul_f32 v[170:171], v[178:179], v[166:167]
	v_pk_mul_f32 v[172:173], v[180:181], v[168:169]
	v_pk_mul_f32 v[174:175], v[182:183], v[162:163]
	v_pk_mul_f32 v[176:177], v[184:185], v[164:165]
	v_pk_mul_f32 v[170:171], v[34:35], v[170:171]
	v_pk_mul_f32 v[172:173], v[36:37], v[172:173]
	v_pk_mul_f32 v[174:175], v[26:27], v[174:175]
	v_pk_mul_f32 v[176:177], v[28:29], v[176:177]
	v_cvt_pk_bf16_f32 v178, v170, v171
	v_cvt_pk_bf16_f32 v179, v172, v173
	v_cvt_pk_bf16_f32 v180, v174, v175
	v_cvt_pk_bf16_f32 v181, v176, v177
	v_add_u32_e32 v182, 0xd2000, v211
	global_store_dwordx4 v182, v[178:181], s[100:101]
	v_cndmask_b32_e64 v170, v18, v22, s[38:39]
	v_cndmask_b32_e64 v171, v19, v23, s[38:39]
	v_cndmask_b32_e64 v172, v20, v24, s[38:39]
	v_cndmask_b32_e64 v173, v21, v25, s[38:39]
	v_cndmask_b32_e64 v174, v6, v10, s[38:39]
	v_cndmask_b32_e64 v175, v7, v11, s[38:39]
	v_cndmask_b32_e64 v176, v8, v12, s[38:39]
	v_cndmask_b32_e64 v177, v9, v13, s[38:39]
	v_cndmask_b32_e64 v166, v18, v22, s[40:41]
	v_cndmask_b32_e64 v167, v19, v23, s[40:41]
	v_cndmask_b32_e64 v168, v20, v24, s[40:41]
	v_cndmask_b32_e64 v169, v21, v25, s[40:41]
	v_cndmask_b32_e64 v162, v6, v10, s[40:41]
	v_cndmask_b32_e64 v163, v7, v11, s[40:41]
	v_cndmask_b32_e64 v164, v8, v12, s[40:41]
	v_cndmask_b32_e64 v165, v9, v13, s[40:41]
	v_pk_fma_f32 v[178:179], v[126:127], v[18:19], v[130:131]
	v_pk_fma_f32 v[180:181], v[128:129], v[20:21], v[132:133]
	v_pk_fma_f32 v[182:183], v[118:119], v[6:7], v[110:111]
	v_pk_fma_f32 v[184:185], v[120:121], v[8:9], v[112:113]
	v_fmac_f32_dpp v178, v166, v134 row_ror:1 row_mask:0xf bank_mask:0xf
	v_fmac_f32_dpp v179, v167, v135 row_ror:1 row_mask:0xf bank_mask:0xf
	v_fmac_f32_dpp v180, v168, v136 row_ror:1 row_mask:0xf bank_mask:0xf
	v_fmac_f32_dpp v181, v169, v137 row_ror:1 row_mask:0xf bank_mask:0xf
	v_fmac_f32_dpp v182, v162, v114 row_ror:1 row_mask:0xf bank_mask:0xf
	v_fmac_f32_dpp v183, v163, v115 row_ror:1 row_mask:0xf bank_mask:0xf
	v_fmac_f32_dpp v184, v164, v116 row_ror:1 row_mask:0xf bank_mask:0xf
	v_fmac_f32_dpp v185, v165, v117 row_ror:1 row_mask:0xf bank_mask:0xf
	v_fmac_f32_dpp v178, v170, v122 row_ror:2 row_mask:0xf bank_mask:0xf
	v_fmac_f32_dpp v179, v171, v123 row_ror:2 row_mask:0xf bank_mask:0xf
	v_fmac_f32_dpp v180, v172, v124 row_ror:2 row_mask:0xf bank_mask:0xf
	v_fmac_f32_dpp v181, v173, v125 row_ror:2 row_mask:0xf bank_mask:0xf
	v_fmac_f32_dpp v182, v174, v106 row_ror:2 row_mask:0xf bank_mask:0xf
	v_fmac_f32_dpp v183, v175, v107 row_ror:2 row_mask:0xf bank_mask:0xf
	v_fmac_f32_dpp v184, v176, v108 row_ror:2 row_mask:0xf bank_mask:0xf
	v_fmac_f32_dpp v185, v177, v109 row_ror:2 row_mask:0xf bank_mask:0xf
	v_pk_mul_f32 v[166:167], v[178:179], v[188:189]
	v_pk_mul_f32 v[168:169], v[180:181], v[188:189]
	v_pk_mul_f32 v[162:163], v[182:183], v[188:189]
	v_pk_mul_f32 v[164:165], v[184:185], v[188:189]
	v_exp_f32_e32 v166, v166
	v_exp_f32_e32 v167, v167
	v_exp_f32_e32 v168, v168
	v_exp_f32_e32 v169, v169
	v_exp_f32_e32 v162, v162
	v_exp_f32_e32 v163, v163
	v_exp_f32_e32 v164, v164
	v_exp_f32_e32 v165, v165
	v_pk_add_f32 v[166:167], v[166:167], v[212:213]
	v_pk_add_f32 v[168:169], v[168:169], v[212:213]
	v_pk_add_f32 v[162:163], v[162:163], v[212:213]
	v_pk_add_f32 v[164:165], v[164:165], v[212:213]
	v_rcp_f32_e32 v166, v166
	v_rcp_f32_e32 v167, v167
	v_rcp_f32_e32 v168, v168
	v_rcp_f32_e32 v169, v169
	v_rcp_f32_e32 v162, v162
	v_rcp_f32_e32 v163, v163
	v_rcp_f32_e32 v164, v164
	v_rcp_f32_e32 v165, v165
	v_pk_mul_f32 v[170:171], v[178:179], v[166:167]
	v_pk_mul_f32 v[172:173], v[180:181], v[168:169]
	v_pk_mul_f32 v[174:175], v[182:183], v[162:163]
	v_pk_mul_f32 v[176:177], v[184:185], v[164:165]
	v_pk_mul_f32 v[170:171], v[14:15], v[170:171]
	v_pk_mul_f32 v[172:173], v[16:17], v[172:173]
	v_pk_mul_f32 v[174:175], v[2:3], v[174:175]
	v_pk_mul_f32 v[176:177], v[4:5], v[176:177]
	v_cvt_pk_bf16_f32 v178, v170, v171
	v_cvt_pk_bf16_f32 v179, v172, v173
	v_cvt_pk_bf16_f32 v180, v174, v175
	v_cvt_pk_bf16_f32 v181, v176, v177
	v_add_u32_e32 v182, 0xe7000, v211
	global_store_dwordx4 v182, v[178:181], s[100:101]
	s_branch .LBB0_1051
